# GLA scan: one value slice per workgroup on all 256 workgroups (halves per-CU LDS traffic), waves 0-3 own the state tiles and the output, waves 4-7 only stream operands
# baseline (speedup 1.0000x reference)
.LBB0_153:
	s_andn2_b64 vcc, exec, s[0:1]
	s_cbranch_vccnz .LBB0_176
	s_and_b32 s0, s2, 7
	s_lshr_b32 s1, s2, 3
	s_and_b32 s5, s1, 3
	s_lshl_b32 s0, s0, 2
	s_add_i32 s0, s0, s5
	s_lshr_b32 s1, s1, 2
	v_lshrrev_b32_e32 v92, 6, v220
	s_nop 0
	v_readfirstlane_b32 s5, v92
	s_nop 0
	s_and_b32 s7, s5, 3
	s_lshr_b32 s9, s5, 2
	s_movk_i32 s14, 0x110
	s_movk_i32 s15, 0x90
	s_movk_i32 s45, 0x1a00
	v_and_b32_e32 v92, 15, v227
	v_lshrrev_b32_e32 v93, 4, v227
	v_and_b32_e32 v94, 31, v227
	v_lshrrev_b32_e32 v95, 5, v227
	s_mov_b32 s50, 91136
	s_lshl_b32 s51, s7, 6
	s_add_i32 s51, s51, s50
	v_mul_u32_u24_e32 v164, s14, v94
	v_lshl_add_u32 v164, v95, 3, v164
	v_add_u32_e32 v164, s51, v164
	s_lshl_b32 s50, s7, 7
	s_add_i32 s50, s50, 35840
	v_lshlrev_b32_e32 v208, 4, v95
	v_add_u32_e32 v208, s50, v208
	s_mul_i32 s50, s7, 4608
	s_add_i32 s50, s50, 17408
	v_mul_u32_u24_e32 v209, s15, v94
	v_lshl_add_u32 v209, v95, 4, v209
	v_add_u32_e32 v209, s50, v209
	s_mov_b32 s50, 36352
	v_mul_u32_u24_e32 v210, s15, v94
	v_lshl_add_u32 v210, v95, 4, v210
	v_add_u32_e32 v210, s50, v210
	v_mov_b32_e32 v0, 0
	v_mov_b32_e32 v1, 0
	v_mov_b32_e32 v2, 0
	v_mov_b32_e32 v3, 0
	v_mov_b32_e32 v4, 0
	v_mov_b32_e32 v5, 0
	v_mov_b32_e32 v6, 0
	v_mov_b32_e32 v7, 0
	v_mov_b32_e32 v8, 0
	v_mov_b32_e32 v9, 0
	v_mov_b32_e32 v10, 0
	v_mov_b32_e32 v11, 0
	v_mov_b32_e32 v12, 0
	v_mov_b32_e32 v13, 0
	v_mov_b32_e32 v14, 0
	v_mov_b32_e32 v15, 0
	s_mov_b32 s44, 0
	s_cmp_eq_u32 s9, 0
	s_cbranch_scc1 .Lsc_osetup
	s_lshl_b32 s14, s0, 20
	s_add_u32 s24, s92, s14
	s_addc_u32 s25, s93, 0
	s_add_u32 s28, s24, 0x2000000
	s_addc_u32 s29, s25, 0
	s_add_u32 s24, s24, 0x1000
	s_addc_u32 s25, s25, 0
	s_add_u32 s46, s24, 0x2000
	s_addc_u32 s47, s25, 0
	s_add_u32 s28, s28, 0x1000
	s_addc_u32 s29, s29, 0
	s_add_u32 s48, s28, 0x2000
	s_addc_u32 s49, s29, 0
	s_lshl_b32 s14, s0, 15
	s_add_u32 s14, s14, 0x1fdbb400
	s_add_u32 s38, s20, s14
	s_addc_u32 s39, s21, 0
	s_lshl_b32 s14, s0, 21
	s_add_u32 s15, s14, 0x1cdc4000
	s_sub_u32 s14, s14, 0x3000000
	s_add_u32 s14, s14, 0x29c4000
	s_cmp_lt_u32 s0, 24
	s_cselect_b32 s14, s15, s14
	s_lshl_b32 s15, s1, 12
	s_add_u32 s14, s14, s15
	s_add_u32 s14, s14, 0x1000
	s_add_u32 s40, s20, s14
	s_addc_u32 s41, s21, 0
	s_movk_i32 s14, 0x110
	s_movk_i32 s15, 0x90
	v_and_b32_e32 v92, 0xff, v220
	v_lshlrev_b32_e32 v236, 4, v92
	v_and_b32_e32 v93, 31, v92
	v_lshlrev_b32_e32 v239, 4, v93
	v_add_u32_e32 v239, 35840, v239
	v_lshrrev_b32_e32 v93, 4, v92
	v_and_b32_e32 v94, 15, v92
	v_lshlrev_b32_e32 v94, 4, v94
	v_mad_u32_u24 v237, v93, s14, v94
	v_lshrrev_b32_e32 v93, 3, v92
	v_and_b32_e32 v94, 7, v92
	v_lshlrev_b32_e32 v94, 4, v94
	v_mad_u32_u24 v238, v93, s15, v94
	v_add_u32_e32 v166, 36352, v238
	v_add_u32_e32 v238, 17408, v238
	global_load_dwordx4 v[24:27], v236, s[24:25] offset:-4096
	global_load_dwordx4 v[28:31], v236, s[24:25]
	global_load_dwordx4 v[32:35], v236, s[46:47] offset:-4096
	global_load_dwordx4 v[36:39], v236, s[46:47]
	global_load_dwordx4 v[40:43], v236, s[28:29] offset:-4096
	global_load_dwordx4 v[44:47], v236, s[28:29]
	global_load_dwordx4 v[48:51], v236, s[48:49] offset:-4096
	global_load_dwordx4 v[52:55], v236, s[48:49]
	global_load_dwordx4 v[56:59], v236, s[40:41] offset:-4096
	global_load_dwordx4 v[60:63], v239, s[38:39]
	s_add_u32 s24, s24, 0x4000
	s_addc_u32 s25, s25, 0
	s_add_u32 s46, s46, 0x4000
	s_addc_u32 s47, s47, 0
	s_add_u32 s28, s28, 0x4000
	s_addc_u32 s29, s29, 0
	s_add_u32 s48, s48, 0x4000
	s_addc_u32 s49, s49, 0
	s_add_u32 s40, s40, 0x8000
	s_addc_u32 s41, s41, 0
	s_add_u32 s38, s38, 0x200
	s_addc_u32 s39, s39, 0
	global_load_dwordx4 v[64:67], v236, s[24:25] offset:-4096
	global_load_dwordx4 v[68:71], v236, s[24:25]
	global_load_dwordx4 v[72:75], v236, s[46:47] offset:-4096
	global_load_dwordx4 v[76:79], v236, s[46:47]
	global_load_dwordx4 v[80:83], v236, s[28:29] offset:-4096
	global_load_dwordx4 v[84:87], v236, s[28:29]
	global_load_dwordx4 v[88:91], v236, s[48:49] offset:-4096
	global_load_dwordx4 v[92:95], v236, s[48:49]
	global_load_dwordx4 v[144:147], v236, s[40:41] offset:-4096
	global_load_dwordx4 v[148:151], v239, s[38:39]
	s_add_u32 s24, s24, 0x4000
	s_addc_u32 s25, s25, 0
	s_add_u32 s46, s46, 0x4000
	s_addc_u32 s47, s47, 0
	s_add_u32 s28, s28, 0x4000
	s_addc_u32 s29, s29, 0
	s_add_u32 s48, s48, 0x4000
	s_addc_u32 s49, s49, 0
	s_add_u32 s40, s40, 0x8000
	s_addc_u32 s41, s41, 0
	s_add_u32 s38, s38, 0x200
	s_addc_u32 s39, s39, 0
	global_load_dwordx4 v[152:155], v236, s[24:25] offset:-4096
	global_load_dwordx4 v[156:159], v236, s[24:25]
	global_load_dwordx4 v[160:163], v236, s[46:47] offset:-4096
	global_load_dwordx4 v[172:175], v236, s[46:47]
	global_load_dwordx4 v[180:183], v236, s[28:29] offset:-4096
	global_load_dwordx4 v[184:187], v236, s[28:29]
	global_load_dwordx4 v[188:191], v236, s[48:49] offset:-4096
	global_load_dwordx4 v[192:195], v236, s[48:49]
	global_load_dwordx4 v[196:199], v236, s[40:41] offset:-4096
	global_load_dwordx4 v[200:203], v239, s[38:39]
	s_add_u32 s24, s24, 0x4000
	s_addc_u32 s25, s25, 0
	s_add_u32 s46, s46, 0x4000
	s_addc_u32 s47, s47, 0
	s_add_u32 s28, s28, 0x4000
	s_addc_u32 s29, s29, 0
	s_add_u32 s48, s48, 0x4000
	s_addc_u32 s49, s49, 0
	s_add_u32 s40, s40, 0x8000
	s_addc_u32 s41, s41, 0
	s_add_u32 s38, s38, 0x200
	s_addc_u32 s39, s39, 0
	s_waitcnt vmcnt(20)
	ds_write_b128 v237, v[24:27] offset:0
	ds_write_b128 v237, v[28:31] offset:4352
	ds_write_b128 v237, v[32:35] offset:8704
	ds_write_b128 v237, v[36:39] offset:13056
	ds_write_b128 v238, v[40:43] offset:0
	ds_write_b128 v238, v[44:47] offset:4608
	ds_write_b128 v238, v[48:51] offset:9216
	ds_write_b128 v238, v[52:55] offset:13824
	ds_write_b128 v166, v[56:59] offset:0
	ds_write_b128 v239, v[60:63] offset:0
	s_waitcnt lgkmcnt(0)
	s_barrier
.Lsc_lloop:
.Lsc_lbody0:
	global_load_dwordx4 v[24:27], v236, s[24:25] offset:-4096
	global_load_dwordx4 v[28:31], v236, s[24:25]
	global_load_dwordx4 v[32:35], v236, s[46:47] offset:-4096
	global_load_dwordx4 v[36:39], v236, s[46:47]
	global_load_dwordx4 v[40:43], v236, s[28:29] offset:-4096
	global_load_dwordx4 v[44:47], v236, s[28:29]
	global_load_dwordx4 v[48:51], v236, s[48:49] offset:-4096
	global_load_dwordx4 v[52:55], v236, s[48:49]
	global_load_dwordx4 v[56:59], v236, s[40:41] offset:-4096
	global_load_dwordx4 v[60:63], v239, s[38:39]
	s_add_u32 s24, s24, 0x4000
	s_addc_u32 s25, s25, 0
	s_add_u32 s46, s46, 0x4000
	s_addc_u32 s47, s47, 0
	s_add_u32 s28, s28, 0x4000
	s_addc_u32 s29, s29, 0
	s_add_u32 s48, s48, 0x4000
	s_addc_u32 s49, s49, 0
	s_add_u32 s40, s40, 0x8000
	s_addc_u32 s41, s41, 0
	s_add_u32 s38, s38, 0x200
	s_addc_u32 s39, s39, 0
	s_waitcnt vmcnt(20)
	ds_write_b128 v237, v[64:67] offset:45568
	ds_write_b128 v237, v[68:71] offset:49920
	ds_write_b128 v237, v[72:75] offset:54272
	ds_write_b128 v237, v[76:79] offset:58624
	ds_write_b128 v238, v[80:83] offset:45568
	ds_write_b128 v238, v[84:87] offset:50176
	ds_write_b128 v238, v[88:91] offset:54784
	ds_write_b128 v238, v[92:95] offset:59392
	ds_write_b128 v166, v[144:147] offset:45568
	ds_write_b128 v239, v[148:151] offset:45568
	s_add_i32 s44, s44, 1
	s_waitcnt lgkmcnt(0)
	s_barrier
.Lsc_lbody1:
	s_cmp_lt_u32 s44, 61
	s_cbranch_scc0 .Lsc_nold_lk1
	global_load_dwordx4 v[64:67], v236, s[24:25] offset:-4096
	global_load_dwordx4 v[68:71], v236, s[24:25]
	global_load_dwordx4 v[72:75], v236, s[46:47] offset:-4096
	global_load_dwordx4 v[76:79], v236, s[46:47]
	global_load_dwordx4 v[80:83], v236, s[28:29] offset:-4096
	global_load_dwordx4 v[84:87], v236, s[28:29]
	global_load_dwordx4 v[88:91], v236, s[48:49] offset:-4096
	global_load_dwordx4 v[92:95], v236, s[48:49]
	global_load_dwordx4 v[144:147], v236, s[40:41] offset:-4096
	global_load_dwordx4 v[148:151], v239, s[38:39]
	s_add_u32 s24, s24, 0x4000
	s_addc_u32 s25, s25, 0
	s_add_u32 s46, s46, 0x4000
	s_addc_u32 s47, s47, 0
	s_add_u32 s28, s28, 0x4000
	s_addc_u32 s29, s29, 0
	s_add_u32 s48, s48, 0x4000
	s_addc_u32 s49, s49, 0
	s_add_u32 s40, s40, 0x8000
	s_addc_u32 s41, s41, 0
	s_add_u32 s38, s38, 0x200
	s_addc_u32 s39, s39, 0
.Lsc_nold_lk1:
	s_cmp_lt_u32 s44, 61
	s_cbranch_scc1 .Lsc_w22_lk1
	s_waitcnt vmcnt(0)
	s_branch .Lsc_wd_lk1
.Lsc_w22_lk1:
	s_waitcnt vmcnt(20)
.Lsc_wd_lk1:
	ds_write_b128 v237, v[152:155] offset:0
	ds_write_b128 v237, v[156:159] offset:4352
	ds_write_b128 v237, v[160:163] offset:8704
	ds_write_b128 v237, v[172:175] offset:13056
	ds_write_b128 v238, v[180:183] offset:0
	ds_write_b128 v238, v[184:187] offset:4608
	ds_write_b128 v238, v[188:191] offset:9216
	ds_write_b128 v238, v[192:195] offset:13824
	ds_write_b128 v166, v[196:199] offset:0
	ds_write_b128 v239, v[200:203] offset:0
	s_add_i32 s44, s44, 1
	s_waitcnt lgkmcnt(0)
	s_barrier
.Lsc_lbody2:
	s_cmp_lt_u32 s44, 61
	s_cbranch_scc0 .Lsc_nold_lk2
	global_load_dwordx4 v[152:155], v236, s[24:25] offset:-4096
	global_load_dwordx4 v[156:159], v236, s[24:25]
	global_load_dwordx4 v[160:163], v236, s[46:47] offset:-4096
	global_load_dwordx4 v[172:175], v236, s[46:47]
	global_load_dwordx4 v[180:183], v236, s[28:29] offset:-4096
	global_load_dwordx4 v[184:187], v236, s[28:29]
	global_load_dwordx4 v[188:191], v236, s[48:49] offset:-4096
	global_load_dwordx4 v[192:195], v236, s[48:49]
	global_load_dwordx4 v[196:199], v236, s[40:41] offset:-4096
	global_load_dwordx4 v[200:203], v239, s[38:39]
	s_add_u32 s24, s24, 0x4000
	s_addc_u32 s25, s25, 0
	s_add_u32 s46, s46, 0x4000
	s_addc_u32 s47, s47, 0
	s_add_u32 s28, s28, 0x4000
	s_addc_u32 s29, s29, 0
	s_add_u32 s48, s48, 0x4000
	s_addc_u32 s49, s49, 0
	s_add_u32 s40, s40, 0x8000
	s_addc_u32 s41, s41, 0
	s_add_u32 s38, s38, 0x200
	s_addc_u32 s39, s39, 0

.Lsc_wd_lk2:
	ds_write_b128 v237, v[24:27] offset:45568
	ds_write_b128 v237, v[28:31] offset:49920
	ds_write_b128 v237, v[32:35] offset:54272
	ds_write_b128 v237, v[36:39] offset:58624
	ds_write_b128 v238, v[40:43] offset:45568
	ds_write_b128 v238, v[44:47] offset:50176
	ds_write_b128 v238, v[48:51] offset:54784
	ds_write_b128 v238, v[52:55] offset:59392
	ds_write_b128 v166, v[56:59] offset:45568
	ds_write_b128 v239, v[60:63] offset:45568
	s_add_i32 s44, s44, 1
	s_waitcnt lgkmcnt(0)
	s_barrier
.Lsc_lbody3:
	s_cmp_lt_u32 s44, 61
	s_cbranch_scc0 .Lsc_nold_lk3
	global_load_dwordx4 v[24:27], v236, s[24:25] offset:-4096
	global_load_dwordx4 v[28:31], v236, s[24:25]
	global_load_dwordx4 v[32:35], v236, s[46:47] offset:-4096
	global_load_dwordx4 v[36:39], v236, s[46:47]
	global_load_dwordx4 v[40:43], v236, s[28:29] offset:-4096
	global_load_dwordx4 v[44:47], v236, s[28:29]
	global_load_dwordx4 v[48:51], v236, s[48:49] offset:-4096
	global_load_dwordx4 v[52:55], v236, s[48:49]
	global_load_dwordx4 v[56:59], v236, s[40:41] offset:-4096
	global_load_dwordx4 v[60:63], v239, s[38:39]
	s_add_u32 s24, s24, 0x4000
	s_addc_u32 s25, s25, 0
	s_add_u32 s46, s46, 0x4000
	s_addc_u32 s47, s47, 0
	s_add_u32 s28, s28, 0x4000
	s_addc_u32 s29, s29, 0
	s_add_u32 s48, s48, 0x4000
	s_addc_u32 s49, s49, 0
	s_add_u32 s40, s40, 0x8000
	s_addc_u32 s41, s41, 0
	s_add_u32 s38, s38, 0x200
	s_addc_u32 s39, s39, 0
.Lsc_nold_lk3:
	s_cmp_lt_u32 s44, 63
	s_cbranch_scc0 .Lsc_nostage_lk3
	s_cmp_lt_u32 s44, 61
	s_cbranch_scc1 .Lsc_w22_lk3
	s_waitcnt vmcnt(0)
	s_branch .Lsc_wd_lk3

.Lsc_wd_lk3:
	ds_write_b128 v237, v[64:67] offset:0
	ds_write_b128 v237, v[68:71] offset:4352
	ds_write_b128 v237, v[72:75] offset:8704
	ds_write_b128 v237, v[76:79] offset:13056
	ds_write_b128 v238, v[80:83] offset:0
	ds_write_b128 v238, v[84:87] offset:4608
	ds_write_b128 v238, v[88:91] offset:9216
	ds_write_b128 v238, v[92:95] offset:13824
	ds_write_b128 v166, v[144:147] offset:0
	ds_write_b128 v239, v[148:151] offset:0

.Lsc_lbody4:
	global_load_dwordx4 v[64:67], v236, s[24:25] offset:-4096
	global_load_dwordx4 v[68:71], v236, s[24:25]
	global_load_dwordx4 v[72:75], v236, s[46:47] offset:-4096
	global_load_dwordx4 v[76:79], v236, s[46:47]
	global_load_dwordx4 v[80:83], v236, s[28:29] offset:-4096
	global_load_dwordx4 v[84:87], v236, s[28:29]
	global_load_dwordx4 v[88:91], v236, s[48:49] offset:-4096
	global_load_dwordx4 v[92:95], v236, s[48:49]
	global_load_dwordx4 v[144:147], v236, s[40:41] offset:-4096
	global_load_dwordx4 v[148:151], v239, s[38:39]
	s_add_u32 s24, s24, 0x4000
	s_addc_u32 s25, s25, 0
	s_add_u32 s46, s46, 0x4000
	s_addc_u32 s47, s47, 0
	s_add_u32 s28, s28, 0x4000
	s_addc_u32 s29, s29, 0
	s_add_u32 s48, s48, 0x4000
	s_addc_u32 s49, s49, 0
	s_add_u32 s40, s40, 0x8000
	s_addc_u32 s41, s41, 0
	s_add_u32 s38, s38, 0x200
	s_addc_u32 s39, s39, 0
	s_waitcnt vmcnt(20)
	ds_write_b128 v237, v[152:155] offset:45568
	ds_write_b128 v237, v[156:159] offset:49920
	ds_write_b128 v237, v[160:163] offset:54272
	ds_write_b128 v237, v[172:175] offset:58624
	ds_write_b128 v238, v[180:183] offset:45568
	ds_write_b128 v238, v[184:187] offset:50176
	ds_write_b128 v238, v[188:191] offset:54784
	ds_write_b128 v238, v[192:195] offset:59392
	ds_write_b128 v166, v[196:199] offset:45568
	ds_write_b128 v239, v[200:203] offset:45568
	s_add_i32 s44, s44, 1
	s_waitcnt lgkmcnt(0)
	s_barrier
.Lsc_lbody5:
	global_load_dwordx4 v[152:155], v236, s[24:25] offset:-4096
	global_load_dwordx4 v[156:159], v236, s[24:25]
	global_load_dwordx4 v[160:163], v236, s[46:47] offset:-4096
	global_load_dwordx4 v[172:175], v236, s[46:47]
	global_load_dwordx4 v[180:183], v236, s[28:29] offset:-4096
	global_load_dwordx4 v[184:187], v236, s[28:29]
	global_load_dwordx4 v[188:191], v236, s[48:49] offset:-4096
	global_load_dwordx4 v[192:195], v236, s[48:49]
	global_load_dwordx4 v[196:199], v236, s[40:41] offset:-4096
	global_load_dwordx4 v[200:203], v239, s[38:39]
	s_add_u32 s24, s24, 0x4000
	s_addc_u32 s25, s25, 0
	s_add_u32 s46, s46, 0x4000
	s_addc_u32 s47, s47, 0
	s_add_u32 s28, s28, 0x4000
	s_addc_u32 s29, s29, 0
	s_add_u32 s48, s48, 0x4000
	s_addc_u32 s49, s49, 0
	s_add_u32 s40, s40, 0x8000
	s_addc_u32 s41, s41, 0
	s_add_u32 s38, s38, 0x200
	s_addc_u32 s39, s39, 0
	s_waitcnt vmcnt(20)
	ds_write_b128 v237, v[24:27] offset:0
	ds_write_b128 v237, v[28:31] offset:4352
	ds_write_b128 v237, v[32:35] offset:8704
	ds_write_b128 v237, v[36:39] offset:13056
	ds_write_b128 v238, v[40:43] offset:0
	ds_write_b128 v238, v[44:47] offset:4608
	ds_write_b128 v238, v[48:51] offset:9216
	ds_write_b128 v238, v[52:55] offset:13824
	ds_write_b128 v166, v[56:59] offset:0
	ds_write_b128 v239, v[60:63] offset:0
	s_add_i32 s44, s44, 1
	s_waitcnt lgkmcnt(0)
	s_barrier
	s_branch .Lsc_lloop

.Lsc_osetup:
	s_lshr_b32 s14, s0, 2
	s_mul_i32 s14, s14, 0x1a00000
	s_add_u32 s42, s96, s14
	s_addc_u32 s43, s97, 0
	s_movk_i32 s14, 0x110
	s_lshl_b32 s50, s7, 4
	v_add_u32_e32 v88, s50, v92
	v_mul_u32_u24_e32 v88, s14, v88
	v_lshl_add_u32 v88, v93, 4, v88
	v_add_u32_e32 v90, s50, v92
	v_mul_u32_u24_e32 v90, s45, v90
	s_and_b32 s50, s0, 3
	s_lshl_b32 s50, s50, 9
	s_lshl_b32 s51, s1, 6
	s_add_i32 s50, s50, s51
	v_lshl_add_u32 v90, v93, 4, v90
	v_add_u32_e32 v90, s50, v90
	v_lshrrev_b32_e32 v94, 2, v92
	v_and_b32_e32 v95, 3, v92
	v_lshl_add_u32 v94, v94, 3, v95
	v_mul_u32_u24_e32 v89, s14, v94
	v_lshl_add_u32 v89, v93, 4, v89
	v_add_u32_e32 v89, 91136, v89
	s_barrier
.Lsc_oloop:
.Lsc_obody0:
	ds_read_b128 v[128:131], v208 offset:0
	ds_read_b128 v[132:135], v208 offset:32
	ds_read_b128 v[136:139], v208 offset:64
	ds_read_b128 v[140:143], v208 offset:96
	ds_read_b128 v[96:99], v209 offset:0
	ds_read_b128 v[100:103], v209 offset:32
	ds_read_b128 v[104:107], v209 offset:64
	ds_read_b128 v[108:111], v209 offset:96
	ds_read_b128 v[112:115], v210 offset:0
	ds_read_b128 v[116:119], v210 offset:32
	ds_read_b128 v[120:123], v210 offset:64
	ds_read_b128 v[124:127], v210 offset:96
	v_cvt_pk_bf16_f32 v16, v0, v1
	v_cvt_pk_bf16_f32 v17, v2, v3
	v_cvt_pk_bf16_f32 v18, v4, v5
	v_cvt_pk_bf16_f32 v19, v6, v7
	v_cvt_pk_bf16_f32 v20, v8, v9
	v_cvt_pk_bf16_f32 v21, v10, v11
	v_cvt_pk_bf16_f32 v22, v12, v13
	v_cvt_pk_bf16_f32 v23, v14, v15
	s_waitcnt lgkmcnt(8)
	v_mul_f32_e32 v0, v0, v128
	v_mul_f32_e32 v1, v1, v129
	v_mul_f32_e32 v2, v2, v130
	v_mul_f32_e32 v3, v3, v131
	v_mul_f32_e32 v4, v4, v132
	v_mul_f32_e32 v5, v5, v133
	v_mul_f32_e32 v6, v6, v134
	v_mul_f32_e32 v7, v7, v135
	v_mul_f32_e32 v8, v8, v136
	v_mul_f32_e32 v9, v9, v137
	v_mul_f32_e32 v10, v10, v138
	v_mul_f32_e32 v11, v11, v139
	v_mul_f32_e32 v12, v12, v140
	v_mul_f32_e32 v13, v13, v141
	v_mul_f32_e32 v14, v14, v142
	v_mul_f32_e32 v15, v15, v143
	s_waitcnt lgkmcnt(0)
	s_nop 1
	v_mfma_f32_32x32x16_bf16 v[0:15], v[96:99], v[112:115], v[0:15]
	ds_read_b128 v[40:43], v89 offset:17408
	ds_read_b128 v[44:47], v89 offset:17472
	ds_read_b128 v[48:51], v89 offset:17536
	ds_read_b128 v[52:55], v89 offset:17600
	v_mfma_f32_32x32x16_bf16 v[0:15], v[100:103], v[116:119], v[0:15]
	ds_read_b128 v[128:131], v89 offset:18496
	ds_read_b128 v[132:135], v89 offset:18560
	ds_read_b128 v[136:139], v89 offset:18624
	ds_read_b128 v[140:143], v89 offset:18688
	v_mfma_f32_32x32x16_bf16 v[0:15], v[104:107], v[120:123], v[0:15]
	ds_write_b64 v164, v[16:17] offset:0
	ds_write_b64 v164, v[18:19] offset:16
	ds_write_b64 v164, v[20:21] offset:32
	ds_write_b64 v164, v[22:23] offset:48
	v_mfma_f32_32x32x16_bf16 v[0:15], v[108:111], v[124:127], v[0:15]
	s_waitcnt lgkmcnt(8)
	v_mfma_f32_16x16x32_bf16 v[24:27], v[40:43], v[72:75], 0
	v_mfma_f32_16x16x32_bf16 v[24:27], v[44:47], v[76:79], v[24:27]
	v_mfma_f32_16x16x32_bf16 v[24:27], v[48:51], v[80:83], v[24:27]
	v_mfma_f32_16x16x32_bf16 v[24:27], v[52:55], v[84:87], v[24:27]
	ds_read_b128 v[56:59], v88 offset:0
	ds_read_b128 v[60:63], v88 offset:64
	ds_read_b128 v[64:67], v88 offset:128
	ds_read_b128 v[68:71], v88 offset:192
	s_waitcnt lgkmcnt(8)
	v_mfma_f32_16x16x32_bf16 v[28:31], v[128:131], v[72:75], 0
	v_mfma_f32_16x16x32_bf16 v[28:31], v[132:135], v[76:79], v[28:31]
	v_mfma_f32_16x16x32_bf16 v[28:31], v[136:139], v[80:83], v[28:31]
	v_mfma_f32_16x16x32_bf16 v[28:31], v[140:143], v[84:87], v[28:31]
	s_nop 7
	s_cmp_eq_u32 s44, 0
	s_cbranch_scc1 .Lsc_nost_ok0
	v_cvt_pk_bf16_f32 v24, v24, v25
	v_cvt_pk_bf16_f32 v25, v26, v27
	v_cvt_pk_bf16_f32 v26, v28, v29
	v_cvt_pk_bf16_f32 v27, v30, v31
	global_store_dwordx4 v90, v[24:27], s[42:43]
	s_add_u32 s42, s42, 0x68000
	s_addc_u32 s43, s43, 0

.Lsc_obody1:
	ds_read_b128 v[128:131], v208 offset:45568
	ds_read_b128 v[132:135], v208 offset:45600
	ds_read_b128 v[136:139], v208 offset:45632
	ds_read_b128 v[140:143], v208 offset:45664
	ds_read_b128 v[96:99], v209 offset:45568
	ds_read_b128 v[100:103], v209 offset:45600
	ds_read_b128 v[104:107], v209 offset:45632
	ds_read_b128 v[108:111], v209 offset:45664
	ds_read_b128 v[112:115], v210 offset:45568
	ds_read_b128 v[116:119], v210 offset:45600
	ds_read_b128 v[120:123], v210 offset:45632
	ds_read_b128 v[124:127], v210 offset:45664
	v_cvt_pk_bf16_f32 v16, v0, v1
	v_cvt_pk_bf16_f32 v17, v2, v3
	v_cvt_pk_bf16_f32 v18, v4, v5
	v_cvt_pk_bf16_f32 v19, v6, v7
	v_cvt_pk_bf16_f32 v20, v8, v9
	v_cvt_pk_bf16_f32 v21, v10, v11
	v_cvt_pk_bf16_f32 v22, v12, v13
	v_cvt_pk_bf16_f32 v23, v14, v15
	s_waitcnt lgkmcnt(8)
	v_mul_f32_e32 v0, v0, v128
	v_mul_f32_e32 v1, v1, v129
	v_mul_f32_e32 v2, v2, v130
	v_mul_f32_e32 v3, v3, v131
	v_mul_f32_e32 v4, v4, v132
	v_mul_f32_e32 v5, v5, v133
	v_mul_f32_e32 v6, v6, v134
	v_mul_f32_e32 v7, v7, v135
	v_mul_f32_e32 v8, v8, v136
	v_mul_f32_e32 v9, v9, v137
	v_mul_f32_e32 v10, v10, v138
	v_mul_f32_e32 v11, v11, v139
	v_mul_f32_e32 v12, v12, v140
	v_mul_f32_e32 v13, v13, v141
	v_mul_f32_e32 v14, v14, v142
	v_mul_f32_e32 v15, v15, v143
	s_waitcnt lgkmcnt(0)
	s_nop 1
	v_mfma_f32_32x32x16_bf16 v[0:15], v[96:99], v[112:115], v[0:15]
	ds_read_b128 v[40:43], v89 offset:0
	ds_read_b128 v[44:47], v89 offset:64
	ds_read_b128 v[48:51], v89 offset:128
	ds_read_b128 v[52:55], v89 offset:192
	v_mfma_f32_32x32x16_bf16 v[0:15], v[100:103], v[116:119], v[0:15]
	ds_read_b128 v[128:131], v89 offset:1088
	ds_read_b128 v[132:135], v89 offset:1152
	ds_read_b128 v[136:139], v89 offset:1216
	ds_read_b128 v[140:143], v89 offset:1280
	v_mfma_f32_32x32x16_bf16 v[0:15], v[104:107], v[120:123], v[0:15]
	ds_write_b64 v164, v[16:17] offset:17408
	ds_write_b64 v164, v[18:19] offset:17424
	ds_write_b64 v164, v[20:21] offset:17440
	ds_write_b64 v164, v[22:23] offset:17456
	v_mfma_f32_32x32x16_bf16 v[0:15], v[108:111], v[124:127], v[0:15]
	s_waitcnt lgkmcnt(8)
	v_mfma_f32_16x16x32_bf16 v[24:27], v[40:43], v[56:59], 0
	v_mfma_f32_16x16x32_bf16 v[24:27], v[44:47], v[60:63], v[24:27]
	v_mfma_f32_16x16x32_bf16 v[24:27], v[48:51], v[64:67], v[24:27]
	v_mfma_f32_16x16x32_bf16 v[24:27], v[52:55], v[68:71], v[24:27]
	ds_read_b128 v[72:75], v88 offset:45568
	ds_read_b128 v[76:79], v88 offset:45632
	ds_read_b128 v[80:83], v88 offset:45696
	ds_read_b128 v[84:87], v88 offset:45760
	s_waitcnt lgkmcnt(8)
	v_mfma_f32_16x16x32_bf16 v[28:31], v[128:131], v[56:59], 0
	v_mfma_f32_16x16x32_bf16 v[28:31], v[132:135], v[60:63], v[28:31]
	v_mfma_f32_16x16x32_bf16 v[28:31], v[136:139], v[64:67], v[28:31]
	v_mfma_f32_16x16x32_bf16 v[28:31], v[140:143], v[68:71], v[28:31]
	s_nop 7
	v_cvt_pk_bf16_f32 v24, v24, v25
	v_cvt_pk_bf16_f32 v25, v26, v27
	v_cvt_pk_bf16_f32 v26, v28, v29
	v_cvt_pk_bf16_f32 v27, v30, v31
	global_store_dwordx4 v90, v[24:27], s[42:43]
	s_add_u32 s42, s42, 0x68000
	s_addc_u32 s43, s43, 0
	s_add_i32 s44, s44, 1
	s_waitcnt lgkmcnt(0)
	s_barrier
.Lsc_obody2:
	ds_read_b128 v[128:131], v208 offset:0
	ds_read_b128 v[132:135], v208 offset:32
	ds_read_b128 v[136:139], v208 offset:64
	ds_read_b128 v[140:143], v208 offset:96
	ds_read_b128 v[96:99], v209 offset:0
	ds_read_b128 v[100:103], v209 offset:32
	ds_read_b128 v[104:107], v209 offset:64
	ds_read_b128 v[108:111], v209 offset:96
	ds_read_b128 v[112:115], v210 offset:0
	ds_read_b128 v[116:119], v210 offset:32
	ds_read_b128 v[120:123], v210 offset:64
	ds_read_b128 v[124:127], v210 offset:96
	v_cvt_pk_bf16_f32 v16, v0, v1
	v_cvt_pk_bf16_f32 v17, v2, v3
	v_cvt_pk_bf16_f32 v18, v4, v5
	v_cvt_pk_bf16_f32 v19, v6, v7
	v_cvt_pk_bf16_f32 v20, v8, v9
	v_cvt_pk_bf16_f32 v21, v10, v11
	v_cvt_pk_bf16_f32 v22, v12, v13
	v_cvt_pk_bf16_f32 v23, v14, v15
	s_waitcnt lgkmcnt(8)
	v_mul_f32_e32 v0, v0, v128
	v_mul_f32_e32 v1, v1, v129
	v_mul_f32_e32 v2, v2, v130
	v_mul_f32_e32 v3, v3, v131
	v_mul_f32_e32 v4, v4, v132
	v_mul_f32_e32 v5, v5, v133
	v_mul_f32_e32 v6, v6, v134
	v_mul_f32_e32 v7, v7, v135
	v_mul_f32_e32 v8, v8, v136
	v_mul_f32_e32 v9, v9, v137
	v_mul_f32_e32 v10, v10, v138
	v_mul_f32_e32 v11, v11, v139
	v_mul_f32_e32 v12, v12, v140
	v_mul_f32_e32 v13, v13, v141
	v_mul_f32_e32 v14, v14, v142
	v_mul_f32_e32 v15, v15, v143
	s_waitcnt lgkmcnt(0)
	s_nop 1
	v_mfma_f32_32x32x16_bf16 v[0:15], v[96:99], v[112:115], v[0:15]
	ds_read_b128 v[40:43], v89 offset:17408
	ds_read_b128 v[44:47], v89 offset:17472
	ds_read_b128 v[48:51], v89 offset:17536
	ds_read_b128 v[52:55], v89 offset:17600
	v_mfma_f32_32x32x16_bf16 v[0:15], v[100:103], v[116:119], v[0:15]
	ds_read_b128 v[128:131], v89 offset:18496
	ds_read_b128 v[132:135], v89 offset:18560
	ds_read_b128 v[136:139], v89 offset:18624
	ds_read_b128 v[140:143], v89 offset:18688
	v_mfma_f32_32x32x16_bf16 v[0:15], v[104:107], v[120:123], v[0:15]
	ds_write_b64 v164, v[16:17] offset:0
	ds_write_b64 v164, v[18:19] offset:16
	ds_write_b64 v164, v[20:21] offset:32
	ds_write_b64 v164, v[22:23] offset:48
	v_mfma_f32_32x32x16_bf16 v[0:15], v[108:111], v[124:127], v[0:15]
	s_waitcnt lgkmcnt(8)
	v_mfma_f32_16x16x32_bf16 v[24:27], v[40:43], v[72:75], 0
	v_mfma_f32_16x16x32_bf16 v[24:27], v[44:47], v[76:79], v[24:27]
	v_mfma_f32_16x16x32_bf16 v[24:27], v[48:51], v[80:83], v[24:27]
	v_mfma_f32_16x16x32_bf16 v[24:27], v[52:55], v[84:87], v[24:27]
	ds_read_b128 v[56:59], v88 offset:0
	ds_read_b128 v[60:63], v88 offset:64
	ds_read_b128 v[64:67], v88 offset:128
	ds_read_b128 v[68:71], v88 offset:192
	s_waitcnt lgkmcnt(8)
	v_mfma_f32_16x16x32_bf16 v[28:31], v[128:131], v[72:75], 0
	v_mfma_f32_16x16x32_bf16 v[28:31], v[132:135], v[76:79], v[28:31]
	v_mfma_f32_16x16x32_bf16 v[28:31], v[136:139], v[80:83], v[28:31]
	v_mfma_f32_16x16x32_bf16 v[28:31], v[140:143], v[84:87], v[28:31]
	s_nop 7
	v_cvt_pk_bf16_f32 v24, v24, v25
	v_cvt_pk_bf16_f32 v25, v26, v27
	v_cvt_pk_bf16_f32 v26, v28, v29
	v_cvt_pk_bf16_f32 v27, v30, v31
	global_store_dwordx4 v90, v[24:27], s[42:43]
	s_add_u32 s42, s42, 0x68000
	s_addc_u32 s43, s43, 0
	s_add_i32 s44, s44, 1
	s_waitcnt lgkmcnt(0)
	s_barrier
.Lsc_obody3:
	ds_read_b128 v[128:131], v208 offset:45568
	ds_read_b128 v[132:135], v208 offset:45600
	ds_read_b128 v[136:139], v208 offset:45632
	ds_read_b128 v[140:143], v208 offset:45664
	ds_read_b128 v[96:99], v209 offset:45568
	ds_read_b128 v[100:103], v209 offset:45600
	ds_read_b128 v[104:107], v209 offset:45632
	ds_read_b128 v[108:111], v209 offset:45664
	ds_read_b128 v[112:115], v210 offset:45568
	ds_read_b128 v[116:119], v210 offset:45600
	ds_read_b128 v[120:123], v210 offset:45632
	ds_read_b128 v[124:127], v210 offset:45664
	v_cvt_pk_bf16_f32 v16, v0, v1
	v_cvt_pk_bf16_f32 v17, v2, v3
	v_cvt_pk_bf16_f32 v18, v4, v5
	v_cvt_pk_bf16_f32 v19, v6, v7
	v_cvt_pk_bf16_f32 v20, v8, v9
	v_cvt_pk_bf16_f32 v21, v10, v11
	v_cvt_pk_bf16_f32 v22, v12, v13
	v_cvt_pk_bf16_f32 v23, v14, v15
	s_waitcnt lgkmcnt(8)
	v_mul_f32_e32 v0, v0, v128
	v_mul_f32_e32 v1, v1, v129
	v_mul_f32_e32 v2, v2, v130
	v_mul_f32_e32 v3, v3, v131
	v_mul_f32_e32 v4, v4, v132
	v_mul_f32_e32 v5, v5, v133
	v_mul_f32_e32 v6, v6, v134
	v_mul_f32_e32 v7, v7, v135
	v_mul_f32_e32 v8, v8, v136
	v_mul_f32_e32 v9, v9, v137
	v_mul_f32_e32 v10, v10, v138
	v_mul_f32_e32 v11, v11, v139
	v_mul_f32_e32 v12, v12, v140
	v_mul_f32_e32 v13, v13, v141
	v_mul_f32_e32 v14, v14, v142
	v_mul_f32_e32 v15, v15, v143
	s_waitcnt lgkmcnt(0)
	s_nop 1
	v_mfma_f32_32x32x16_bf16 v[0:15], v[96:99], v[112:115], v[0:15]
	ds_read_b128 v[40:43], v89 offset:0
	ds_read_b128 v[44:47], v89 offset:64
	ds_read_b128 v[48:51], v89 offset:128
	ds_read_b128 v[52:55], v89 offset:192
	v_mfma_f32_32x32x16_bf16 v[0:15], v[100:103], v[116:119], v[0:15]
	ds_read_b128 v[128:131], v89 offset:1088
	ds_read_b128 v[132:135], v89 offset:1152
	ds_read_b128 v[136:139], v89 offset:1216
	ds_read_b128 v[140:143], v89 offset:1280
	v_mfma_f32_32x32x16_bf16 v[0:15], v[104:107], v[120:123], v[0:15]
	ds_write_b64 v164, v[16:17] offset:17408
	ds_write_b64 v164, v[18:19] offset:17424
	ds_write_b64 v164, v[20:21] offset:17440
	ds_write_b64 v164, v[22:23] offset:17456
	v_mfma_f32_32x32x16_bf16 v[0:15], v[108:111], v[124:127], v[0:15]
	s_waitcnt lgkmcnt(8)
	v_mfma_f32_16x16x32_bf16 v[24:27], v[40:43], v[56:59], 0
	v_mfma_f32_16x16x32_bf16 v[24:27], v[44:47], v[60:63], v[24:27]
	v_mfma_f32_16x16x32_bf16 v[24:27], v[48:51], v[64:67], v[24:27]
	v_mfma_f32_16x16x32_bf16 v[24:27], v[52:55], v[68:71], v[24:27]
	ds_read_b128 v[72:75], v88 offset:45568
	ds_read_b128 v[76:79], v88 offset:45632
	ds_read_b128 v[80:83], v88 offset:45696
	ds_read_b128 v[84:87], v88 offset:45760
	s_waitcnt lgkmcnt(8)
	v_mfma_f32_16x16x32_bf16 v[28:31], v[128:131], v[56:59], 0
	v_mfma_f32_16x16x32_bf16 v[28:31], v[132:135], v[60:63], v[28:31]
	v_mfma_f32_16x16x32_bf16 v[28:31], v[136:139], v[64:67], v[28:31]
	v_mfma_f32_16x16x32_bf16 v[28:31], v[140:143], v[68:71], v[28:31]
	s_nop 7
	v_cvt_pk_bf16_f32 v24, v24, v25
	v_cvt_pk_bf16_f32 v25, v26, v27
	v_cvt_pk_bf16_f32 v26, v28, v29
	v_cvt_pk_bf16_f32 v27, v30, v31
	global_store_dwordx4 v90, v[24:27], s[42:43]
	s_add_u32 s42, s42, 0x68000
	s_addc_u32 s43, s43, 0
	s_add_i32 s44, s44, 1
	s_waitcnt lgkmcnt(0)
	s_barrier
	s_cmp_eq_u32 s44, 64
	s_cbranch_scc1 .Lsc_oepi

.Lsc_obody5:
	ds_read_b128 v[128:131], v208 offset:45568
	ds_read_b128 v[132:135], v208 offset:45600
	ds_read_b128 v[136:139], v208 offset:45632
	ds_read_b128 v[140:143], v208 offset:45664
	ds_read_b128 v[96:99], v209 offset:45568
	ds_read_b128 v[100:103], v209 offset:45600
	ds_read_b128 v[104:107], v209 offset:45632
	ds_read_b128 v[108:111], v209 offset:45664
	ds_read_b128 v[112:115], v210 offset:45568
	ds_read_b128 v[116:119], v210 offset:45600
	ds_read_b128 v[120:123], v210 offset:45632
	ds_read_b128 v[124:127], v210 offset:45664
	v_cvt_pk_bf16_f32 v16, v0, v1
	v_cvt_pk_bf16_f32 v17, v2, v3
	v_cvt_pk_bf16_f32 v18, v4, v5
	v_cvt_pk_bf16_f32 v19, v6, v7
	v_cvt_pk_bf16_f32 v20, v8, v9
	v_cvt_pk_bf16_f32 v21, v10, v11
	v_cvt_pk_bf16_f32 v22, v12, v13
	v_cvt_pk_bf16_f32 v23, v14, v15
	s_waitcnt lgkmcnt(8)
	v_mul_f32_e32 v0, v0, v128
	v_mul_f32_e32 v1, v1, v129
	v_mul_f32_e32 v2, v2, v130
	v_mul_f32_e32 v3, v3, v131
	v_mul_f32_e32 v4, v4, v132
	v_mul_f32_e32 v5, v5, v133
	v_mul_f32_e32 v6, v6, v134
	v_mul_f32_e32 v7, v7, v135
	v_mul_f32_e32 v8, v8, v136
	v_mul_f32_e32 v9, v9, v137
	v_mul_f32_e32 v10, v10, v138
	v_mul_f32_e32 v11, v11, v139
	v_mul_f32_e32 v12, v12, v140
	v_mul_f32_e32 v13, v13, v141
	v_mul_f32_e32 v14, v14, v142
	v_mul_f32_e32 v15, v15, v143
	s_waitcnt lgkmcnt(0)
	s_nop 1
	v_mfma_f32_32x32x16_bf16 v[0:15], v[96:99], v[112:115], v[0:15]
	ds_read_b128 v[40:43], v89 offset:0
	ds_read_b128 v[44:47], v89 offset:64
	ds_read_b128 v[48:51], v89 offset:128
	ds_read_b128 v[52:55], v89 offset:192
	v_mfma_f32_32x32x16_bf16 v[0:15], v[100:103], v[116:119], v[0:15]
	ds_read_b128 v[128:131], v89 offset:1088
	ds_read_b128 v[132:135], v89 offset:1152
	ds_read_b128 v[136:139], v89 offset:1216
	ds_read_b128 v[140:143], v89 offset:1280
	v_mfma_f32_32x32x16_bf16 v[0:15], v[104:107], v[120:123], v[0:15]
	ds_write_b64 v164, v[16:17] offset:17408
	ds_write_b64 v164, v[18:19] offset:17424
	ds_write_b64 v164, v[20:21] offset:17440
	ds_write_b64 v164, v[22:23] offset:17456
	v_mfma_f32_32x32x16_bf16 v[0:15], v[108:111], v[124:127], v[0:15]
	s_waitcnt lgkmcnt(8)
	v_mfma_f32_16x16x32_bf16 v[24:27], v[40:43], v[56:59], 0
	v_mfma_f32_16x16x32_bf16 v[24:27], v[44:47], v[60:63], v[24:27]
	v_mfma_f32_16x16x32_bf16 v[24:27], v[48:51], v[64:67], v[24:27]
	v_mfma_f32_16x16x32_bf16 v[24:27], v[52:55], v[68:71], v[24:27]
	ds_read_b128 v[72:75], v88 offset:45568
	ds_read_b128 v[76:79], v88 offset:45632
	ds_read_b128 v[80:83], v88 offset:45696
	ds_read_b128 v[84:87], v88 offset:45760
	s_waitcnt lgkmcnt(8)
	v_mfma_f32_16x16x32_bf16 v[28:31], v[128:131], v[56:59], 0
	v_mfma_f32_16x16x32_bf16 v[28:31], v[132:135], v[60:63], v[28:31]
	v_mfma_f32_16x16x32_bf16 v[28:31], v[136:139], v[64:67], v[28:31]
	v_mfma_f32_16x16x32_bf16 v[28:31], v[140:143], v[68:71], v[28:31]
	s_nop 7
	v_cvt_pk_bf16_f32 v24, v24, v25
	v_cvt_pk_bf16_f32 v25, v26, v27
	v_cvt_pk_bf16_f32 v26, v28, v29
	v_cvt_pk_bf16_f32 v27, v30, v31
	global_store_dwordx4 v90, v[24:27], s[42:43]
	s_add_u32 s42, s42, 0x68000
	s_addc_u32 s43, s43, 0
	s_add_i32 s44, s44, 1
	s_waitcnt lgkmcnt(0)
	s_barrier
	s_branch .Lsc_oloop
.Lsc_oepi:
	ds_read_b128 v[40:43], v89 offset:17408
	ds_read_b128 v[44:47], v89 offset:17472
	ds_read_b128 v[48:51], v89 offset:17536
	ds_read_b128 v[52:55], v89 offset:17600
	ds_read_b128 v[128:131], v89 offset:18496
	ds_read_b128 v[132:135], v89 offset:18560
	ds_read_b128 v[136:139], v89 offset:18624
	ds_read_b128 v[140:143], v89 offset:18688
	s_waitcnt lgkmcnt(4)
	v_mfma_f32_16x16x32_bf16 v[24:27], v[40:43], v[72:75], 0
	v_mfma_f32_16x16x32_bf16 v[24:27], v[44:47], v[76:79], v[24:27]
	v_mfma_f32_16x16x32_bf16 v[24:27], v[48:51], v[80:83], v[24:27]
	v_mfma_f32_16x16x32_bf16 v[24:27], v[52:55], v[84:87], v[24:27]
	s_waitcnt lgkmcnt(0)
	v_mfma_f32_16x16x32_bf16 v[28:31], v[128:131], v[72:75], 0
	v_mfma_f32_16x16x32_bf16 v[28:31], v[132:135], v[76:79], v[28:31]
	v_mfma_f32_16x16x32_bf16 v[28:31], v[136:139], v[80:83], v[28:31]
	v_mfma_f32_16x16x32_bf16 v[28:31], v[140:143], v[84:87], v[28:31]
	s_nop 7
	v_cvt_pk_bf16_f32 v24, v24, v25
	v_cvt_pk_bf16_f32 v25, v26, v27
	v_cvt_pk_bf16_f32 v26, v28, v29
	v_cvt_pk_bf16_f32 v27, v30, v31
	global_store_dwordx4 v90, v[24:27], s[42:43]
	s_add_u32 s42, s42, 0x68000
	s_addc_u32 s43, s43, 0
	s_branch .LBB0_176
